# per-XCD barriers now guarded by a run-time check of the workgroup-to-XCD dispatch (falls back to the grid barrier if classes id&7 do not each sit on one XCD)
# speedup vs baseline: 1.0060x; 1.0060x over previous
; #define LAS __attribute__((address_space(3)))
; __device__ __forceinline__ unsigned xb_add(unsigned* p, unsigned v) { return __hip_atomic_fetch_add(p, v, __ATOMIC_RELAXED, __HIP_MEMORY_SCOPE_AGENT); }
; __device__ __forceinline__ unsigned xb_xcc_id() { return (unsigned)__builtin_amdgcn_s_getreg((3 << 11) | 20) & 0xFu; }
; __device__ __forceinline__ XcdBarrier xcd_barrier_post(unsigned* bar, volatile LAS unsigned* st) {
;     XcdBarrier b; b.bar = bar; b.x = xb_xcc_id(); b.st = st;
;     if (threadIdx.x == 0) (void)xb_add(&bar[XB_XCNT(b.x)], 1u);
;     return b;
; __global__ void __launch_bounds__(512, 2) fwd_megakernel(Args a) {
;     extern __shared__ __attribute__((aligned(16))) unsigned char lds_raw[];
;     LAS unsigned char* L = (LAS unsigned char*)lds_raw;
;     volatile LAS unsigned* MISC = (volatile LAS unsigned*)(L + LDS_BYTES - 64);
;     if (threadIdx.x < 16) MISC[threadIdx.x] = 0u;
;     __syncthreads();
;     const XcdBarrier xbar = xcd_barrier_post((unsigned*)(a.ws + WS_CTL), MISC);
_Z14fwd_megakernel4Args:
	s_load_dwordx16 s[64:79], s[0:1], 0x80
	v_and_b32_e32 v238, 0x3ff, v0
	v_writelane_b32 v252, s2, 0
	v_cmp_gt_u32_e32 vcc, 16, v238
	s_and_saveexec_b64 s[2:3], vcc
	v_lshl_add_u32 v1, v238, 2, 0
	v_add_u32_e32 v1, 0x23fc0, v1
	v_mov_b32_e32 v2, 0
	ds_write_b32 v1, v2
	s_or_b64 exec, exec, s[2:3]
	s_load_dwordx16 s[4:19], s[0:1], 0x0
	s_waitcnt lgkmcnt(0)
	s_barrier
	s_getreg_b32 s2, hwreg(HW_REG_XCC_ID, 0, 4)
	v_writelane_b32 v252, s4, 1
	v_cmp_ne_u32_e64 s[96:97], 0, v238
	v_cmp_eq_u32_e64 s[80:81], 0, v238
	v_writelane_b32 v252, s5, 2
	v_writelane_b32 v252, s6, 3
	v_writelane_b32 v252, s7, 4
	v_writelane_b32 v252, s8, 5
	v_writelane_b32 v252, s9, 6
	v_writelane_b32 v252, s10, 7
	v_writelane_b32 v252, s11, 8
	v_writelane_b32 v252, s12, 9
	v_writelane_b32 v252, s13, 10
	v_writelane_b32 v252, s14, 11
	v_writelane_b32 v252, s15, 12
	v_writelane_b32 v252, s16, 13
	v_writelane_b32 v252, s17, 14
	v_writelane_b32 v252, s18, 15
	v_writelane_b32 v252, s19, 16
	s_add_u32 s18, s78, 0x14700000
	s_addc_u32 s19, s79, 0
	s_and_b32 s33, s2, 15
	s_and_saveexec_b64 s[2:3], s[80:81]
	s_cbranch_execz .LBB0_5
	s_mov_b64 s[4:5], exec
	v_mbcnt_lo_u32_b32 v1, s4, 0
	v_mbcnt_hi_u32_b32 v1, s5, v1
	v_cmp_eq_u32_e32 vcc, 0, v1
	s_and_b64 s[6:7], exec, vcc
	s_mov_b64 exec, s[6:7]
	s_cbranch_execz .LBB0_5
	s_lshl_b32 s6, s33, 8
	s_bcnt1_i32_b64 s4, s[4:5]
	v_mov_b32_e32 v1, s6
	v_mov_b32_e32 v2, s4
	global_atomic_add v1, v2, s[18:19] offset:1024
	v_readlane_b32 s6, v252, 0
	s_nop 3
	s_and_b32 s6, s6, 7
	s_lshl_b32 s6, s6, 8
	s_add_u32 s6, s6, 0x4000
	s_lshl_b32 s7, 1, s33
	v_mov_b32_e32 v1, s6
	v_mov_b32_e32 v2, s7
	global_atomic_or v1, v2, s[18:19]

; #define PG8_BAR __builtin_amdgcn_s_barrier()
; template <class Epi, class Sched, bool ALIGN_EPI = false, bool SP2 = false>
; __device__ __forceinline__ void gemm_phase(PG8_LAS unsigned char* lds, const Gemm g, const Sched& S, const Epi& E) {
;     int tid_ = threadIdx.x; asm volatile("" : "+v"(tid_)); const int tid = tid_, wid = __builtin_amdgcn_readfirstlane(tid >> 6), lane = tid & 63, wr = wid >> 2, wc = wid & 3, fr = lane & 15, fq = lane >> 4;
;     const int K = g.K, nt = K / BK;
;     unsigned voffA[2], voffB[2];
; #pragma unroll
;     for (int i = 0; i < 2; ++i) { int R, C; stage_rc(tid * 16 + i * 8192, R, C); const int Rb = Epi::PERM ? ((R & ~31) + perm32(R & 31)) : R;
;         voffA[i] = (unsigned)(R * g.lda + C) * 2u; voffB[i] = (unsigned)(Rb * g.ldb + C) * 2u; }
;     const size_t kstep = (size_t)(BK * 2);
;     const size_t hstepA = (size_t)HALF * g.lda * 2, hstepB = (size_t)HALF * g.ldb * 2;
;     const size_t tstepA = 2 * hstepA, tstepB = 2 * hstepB;
;     const unsigned ldsw = (unsigned)wid * 1024u;
;     const int aoff = lds_byte(wr * 64 + fr, fq * 8), boff = lds_byte(wc * 32 + fr, fq * 8);
;     ...
;     Unit cur, nxt; int ui = 0;
;     if (!S.next(0, cur)) return;
;     f32x4 acc[2][2][4][2];
; #pragma unroll
;     for (int a = 0; a < 2; ++a)
; #pragma unroll
;         for (int b = 0; b < 2; ++b)
; #pragma unroll
;             for (int m = 0; m < 4; ++m)
; #pragma unroll
;                 for (int n = 0; n < 2; ++n) acc[a][b][m][n] = (f32x4){0.f, 0.f, 0.f, 0.f};
;     bf16x8 At[4][2], B0[2][2], B1[2][2];
;     const char* cA = (const char*)g.A + (size_t)cur.pm * tstepA; const char* cB = (const char*)g.Bt + (size_t)cur.pn * tstepB;
;     S.a_ready(cur);
;     if constexpr (SP2) {
;         PG8_STAGE(PG8_SB(0, 0), cB, voffB); PG8_STAGE(PG8_SB(0, 1), cB + hstepB, voffB); PG8_STAGE(PG8_SA(0, 0), cA, voffA); PG8_STAGE(PG8_SA(0, 1), cA + hstepA, voffA);
;         if (wr == 1) PG8_BAR;
;         PG8_WAIT_V(2); PG8_BAR;
;         PG8_STAGE(PG8_SB(1, 0), cB + kstep, voffB); PG8_STAGE(PG8_SA(1, 0), cA + kstep, voffA); PG8_STAGE(PG8_SB(1, 1), cB + hstepB + kstep, voffB);
;         PG8_WAIT_V(6); PG8_BAR;
;     } else {
;         PG8_STAGE(PG8_SB(0, 0), cB, voffB); PG8_STAGE(PG8_SA(0, 0), cA, voffA); PG8_STAGE(PG8_SB(0, 1), cB + hstepB, voffB); PG8_STAGE(PG8_SA(0, 1), cA + hstepA, voffA);
;         if (wr == 1) PG8_BAR;
;         PG8_WAIT_V(4); PG8_BAR;
.LBB0_139:
	v_writelane_b32 v254, s2, 54
	s_mov_b64 s[0:1], 0
	v_mov_b32_e32 v0, v238
	s_mov_b32 s24, s29
	v_readlane_b32 s25, v252, 0
	v_mov_b32_e32 v12, v238
	v_writelane_b32 v254, s3, 55
	v_readlane_b32 s100, v254, 28
	s_nop 3
	s_cmp_lg_u32 s100, 0
	s_cbranch_scc1 .Lmapchk_done
	s_add_u32 s100, s78, 0x14704000
	s_addc_u32 s101, s79, 0
	v_mov_b32_e32 v2, 0
	global_load_dword v3, v2, s[100:101] sc1
	global_load_dword v4, v2, s[100:101] offset:256 sc1
	global_load_dword v5, v2, s[100:101] offset:512 sc1
	global_load_dword v6, v2, s[100:101] offset:768 sc1
	global_load_dword v7, v2, s[100:101] offset:1024 sc1
	global_load_dword v8, v2, s[100:101] offset:1280 sc1
	global_load_dword v9, v2, s[100:101] offset:1536 sc1
	global_load_dword v10, v2, s[100:101] offset:1792 sc1
	s_waitcnt vmcnt(0)
	v_bcnt_u32_b32 v3, v3, 0
	v_subrev_u32_e32 v3, 1, v3
	v_bcnt_u32_b32 v4, v4, 0
	v_subrev_u32_e32 v4, 1, v4
	v_bcnt_u32_b32 v5, v5, 0
	v_subrev_u32_e32 v5, 1, v5
	v_bcnt_u32_b32 v6, v6, 0
	v_subrev_u32_e32 v6, 1, v6
	v_bcnt_u32_b32 v7, v7, 0
	v_subrev_u32_e32 v7, 1, v7
	v_bcnt_u32_b32 v8, v8, 0
	v_subrev_u32_e32 v8, 1, v8
	v_bcnt_u32_b32 v9, v9, 0
	v_subrev_u32_e32 v9, 1, v9
	v_bcnt_u32_b32 v10, v10, 0
	v_subrev_u32_e32 v10, 1, v10
	v_or_b32_e32 v3, v3, v4
	v_or_b32_e32 v3, v3, v5
	v_or_b32_e32 v3, v3, v6
	v_or_b32_e32 v3, v3, v7
	v_or_b32_e32 v3, v3, v8
	v_or_b32_e32 v3, v3, v9
	v_or_b32_e32 v3, v3, v10
	v_readfirstlane_b32 s101, v3
.Lmapchk_done:
	s_cmpk_lt_i32 s25, 0x580
	v_readfirstlane_b32 s6, v12
	s_cbranch_scc0 .LBB0_155
	v_lshlrev_b32_e32 v0, 4, v12
	v_add_u32_e32 v2, 0x2000, v0
	v_ashrrev_i32_e32 v3, 31, v2
	v_lshrrev_b32_e32 v3, 22, v3
	v_add_u32_e32 v3, v2, v3
	v_ashrrev_i32_e32 v10, 10, v3
	v_mul_i32_i24_e32 v3, 0x400, v10
	v_sub_u32_e32 v2, v2, v3
	v_lshrrev_b32_e32 v3, 4, v2
	v_bitop3_b32 v2, v3, v2, 32 bitop3:0x6c
	v_ashrrev_i32_e32 v3, 31, v2
	v_lshrrev_b32_e32 v3, 26, v3
	v_add_u32_e32 v3, v2, v3
	v_lshlrev_b32_e32 v4, 3, v10
	v_ashrrev_i32_e32 v11, 6, v3
	v_and_b32_e32 v4, -16, v4
	v_add_u32_e32 v4, v11, v4
	v_and_b32_e32 v5, 3, v11
	s_mov_b32 s2, 0x1fffe0
	v_lshrrev_b32_e32 v6, 2, v4
	v_lshlrev_b32_e32 v7, 1, v4
	v_and_b32_e32 v3, 0xc0, v3
	v_and_or_b32 v5, v4, s2, v5
	v_and_b32_e32 v6, 4, v6
	v_and_b32_e32 v7, 24, v7
	v_sub_u32_e32 v2, v2, v3
	v_or3_b32 v5, v5, v6, v7
	v_lshlrev_b32_e32 v6, 5, v10
	v_ashrrev_i16_sdwa v2, v241, sext(v2) dst_sel:DWORD dst_unused:UNUSED_PAD src0_sel:DWORD src1_sel:BYTE_0
	v_and_b32_e32 v6, 32, v6
	v_bfe_i32 v13, v2, 0, 16
	v_add_lshl_u32 v2, v6, v13, 1
	v_lshl_add_u32 v146, v5, 11, v2
	v_lshl_add_u32 v148, v4, 11, v2
	v_bfe_i32 v2, v12, 27, 1
	v_lshrrev_b32_e32 v2, 22, v2
	v_add_u32_e32 v2, v0, v2
	v_and_b32_e32 v2, 0xfffffc00, v2
	v_sub_u32_e32 v0, v0, v2
	v_lshrrev_b32_e32 v2, 4, v0
	v_ashrrev_i32_e32 v3, 31, v12
	v_bitop3_b32 v0, v2, v0, 32 bitop3:0x6c
	v_lshrrev_b32_e32 v3, 26, v3
	v_ashrrev_i32_e32 v2, 31, v0
	v_add_u32_e32 v3, v12, v3
	s_add_u32 s0, s78, s0
	v_lshrrev_b32_e32 v2, 26, v2
	v_ashrrev_i32_e32 v15, 6, v3
	s_addc_u32 s1, s79, s1
	v_add_u32_e32 v2, v0, v2
	v_lshlrev_b32_e32 v3, 3, v15
	s_add_u32 s26, s0, 0x4400000
	v_ashrrev_i32_e32 v14, 6, v2
	v_and_b32_e32 v3, -16, v3
	s_addc_u32 s27, s1, 0
	v_add_u32_e32 v3, v14, v3
	v_and_b32_e32 v4, 3, v14
	s_ashr_i32 s29, s25, 31
	v_and_or_b32 v4, v3, s2, v4
	s_lshr_b32 s2, s29, 29
	s_add_i32 s2, s25, s2
	s_ashr_i32 s7, s6, 6
	s_ashr_i32 s3, s2, 3
	s_and_b32 s2, s2, -8
	s_ashr_i32 s8, s6, 8
	s_lshl_b32 s28, s7, 10
	s_sub_i32 s2, s25, s2
	s_cmp_lt_i32 s2, 0
	s_movk_i32 s4, 0xb1
	s_cselect_b32 s4, s4, 0xb0
	s_mul_i32 s2, s4, s2
	s_add_i32 s2, s2, s3
	s_mul_hi_i32 s3, s2, 0x2e8ba2e9
	s_lshr_b32 s4, s3, 31
	s_ashr_i32 s3, s3, 5
	s_add_i32 s3, s3, s4
	s_lshl_b32 s5, s3, 3
	s_mulk_i32 s3, 0xb0
	s_sub_i32 s2, s2, s3
	s_bfe_u32 s3, s2, 0x3001c
	s_add_i32 s3, s2, s3
	s_sext_i32_i16 s4, s3
	s_and_b32 s3, s3, 0xfff8
	s_sub_i32 s2, s2, s3
	s_sext_i32_i16 s2, s2
	v_lshrrev_b32_e32 v5, 2, v3
	v_lshlrev_b32_e32 v6, 1, v3
	v_and_b32_e32 v2, 0xc0, v2
	s_lshr_b32 s4, s4, 3
	s_add_i32 s16, s5, s2
	v_and_b32_e32 v5, 4, v5
	v_and_b32_e32 v6, 24, v6
	v_sub_u32_e32 v0, v0, v2
	s_ashr_i32 s17, s16, 31
	s_bfe_i64 s[10:11], s[4:5], 0x100000
	v_or3_b32 v4, v4, v5, v6
	v_lshlrev_b32_e32 v5, 5, v15
	v_ashrrev_i16_sdwa v0, v241, sext(v0) dst_sel:DWORD dst_unused:UNUSED_PAD src0_sel:DWORD src1_sel:BYTE_0
	s_lshl_b64 s[2:3], s[16:17], 19
	s_lshl_b64 s[10:11], s[10:11], 19
	v_and_b32_e32 v5, 32, v5
	v_bfe_i32 v16, v0, 0, 16
	s_add_u32 s20, s0, s10
	v_add_lshl_u32 v2, v5, v16, 1
	s_addc_u32 s21, s1, s11
	s_add_i32 s30, s28, 0
	v_lshl_add_u32 v0, v4, 11, v2
	s_add_i32 m0, s30, 0x10000
	v_lshl_add_u32 v150, v3, 11, v2
	global_load_lds_dwordx4 v0, s[20:21]
	s_add_i32 m0, s30, 0x12000
	s_add_u32 s10, s20, 0x40000
	global_load_lds_dwordx4 v146, s[20:21]
	s_addc_u32 s11, s21, 0
	s_add_i32 m0, s30, 0x14000
	v_mov_b32_e32 v147, v1
	global_load_lds_dwordx4 v0, s[10:11]
	s_add_i32 m0, s30, 0x16000
	s_add_u32 s18, s26, s2
	s_addc_u32 s19, s27, s3
	s_add_i32 s31, s30, 0x2000
	global_load_lds_dwordx4 v146, s[10:11]
	s_mov_b32 m0, s30
	s_add_u32 s2, s18, 0x40000
	global_load_lds_dwordx4 v150, s[18:19]
	s_mov_b32 m0, s31
	s_addc_u32 s3, s19, 0
	s_add_i32 s34, s30, 0x4000
	global_load_lds_dwordx4 v148, s[18:19]
	s_mov_b32 m0, s34
	s_add_i32 s35, s30, 0x6000
	global_load_lds_dwordx4 v150, s[2:3]
	s_mov_b32 m0, s35
	v_mov_b32_e32 v151, v1
	global_load_lds_dwordx4 v148, s[2:3]
	v_mov_b32_e32 v149, v1
	s_cmp_eq_u32 s8, 1
	v_lshl_add_u64 v[8:9], s[20:21], 0, v[0:1]
	v_lshl_add_u64 v[6:7], s[20:21], 0, v[146:147]
	v_lshl_add_u64 v[2:3], s[18:19], 0, v[150:151]
	s_cselect_b64 s[2:3], -1, 0
	s_cmp_lg_u32 s8, 1
	v_lshl_add_u64 v[4:5], s[18:19], 0, v[148:149]
	s_cbranch_scc1 .LBB0_142
	s_barrier

; __device__ __forceinline__ unsigned xb_ld(unsigned* p)              { return __hip_atomic_load(p, __ATOMIC_RELAXED, __HIP_MEMORY_SCOPE_AGENT); }
; __device__ __forceinline__ unsigned xb_add(unsigned* p, unsigned v) { return __hip_atomic_fetch_add(p, v, __ATOMIC_RELAXED, __HIP_MEMORY_SCOPE_AGENT); }
; #define XB_SPIN(cond, bar) do { unsigned _sp = 0; while (cond) { __builtin_amdgcn_s_sleep(1); \
;     if ((++_sp & 255u) == 0u) { if (xb_ld(&(bar)[XB_TMO])) break; if (_sp > XB_SPIN_CAP) { atomicAdd(&(bar)[XB_TMO], 1u); break; } } } } while (0)
; __device__ __forceinline__ void xcd_barrier(const XcdBarrier& b) {
;     ...
;         const unsigned old = xb_add(&bar[XB_XSUB(b.x)], 1u);
;         const unsigned gen = old / nloc;
;         if (old + 1u == (gen + 1u) * nloc) {
;             __builtin_amdgcn_fence(__ATOMIC_RELEASE, "agent");
;             asm volatile("s_waitcnt vmcnt(0)" ::: "memory");
;             const unsigned og = xb_add(&bar[XB_TOP], 1u);
;             const unsigned tg = og / nx;
;             if (og + 1u == (tg + 1u) * nx) xb_add(&bar[XB_TOPGEN], 1u);
;             else XB_SPIN(xb_ld(&bar[XB_TOPGEN]) == tg, bar);
;             __builtin_amdgcn_fence(__ATOMIC_ACQUIRE, "agent");
;             xb_add(&bar[XB_XGEN(b.x)], 1u);
;             asm volatile("s_waitcnt vmcnt(0)" ::: "memory");
;         } else {
;             XB_SPIN(xb_ld(&bar[XB_XGEN(b.x)]) == gen, bar);
;             __builtin_amdgcn_fence(__ATOMIC_ACQUIRE, "agent");
;             asm volatile("s_waitcnt vmcnt(0)" ::: "memory");
;         }
.LBB0_185:
	s_andn2_saveexec_b64 s[2:3], s[2:3]
	s_cbranch_execz .LBB0_203
	s_cmp_lg_u32 s101, 0
	s_cbranch_scc1 .Llb_grid_1
	s_waitcnt vmcnt(0) lgkmcnt(0)
	buffer_inv sc1
	global_atomic_add v[196:197], v241, off
	s_waitcnt vmcnt(0)
	s_branch .LBB0_203
.Llb_grid_1:
	s_mov_b64 s[4:5], exec
	buffer_wbl2 sc1
	s_waitcnt lgkmcnt(0)
	s_waitcnt vmcnt(0)
	v_mbcnt_lo_u32_b32 v0, s4, 0
	v_mbcnt_hi_u32_b32 v0, s5, v0
	v_cmp_eq_u32_e32 vcc, 0, v0
	s_and_saveexec_b64 s[6:7], vcc
	s_cbranch_execz .LBB0_188
	s_bcnt1_i32_b64 s4, s[4:5]
	v_mov_b32_e32 v3, s4
	v_readlane_b32 s4, v253, 52
	v_readlane_b32 s5, v253, 53
	s_nop 4
	global_atomic_add v3, v1, v3, s[4:5] sc0
